# V tile staged in accumulator key order: P lane-half swaps removed; widened attention epilogue stores via LDS transpose
# speedup vs baseline: 1.0120x; 1.0120x over previous
; __device__ __forceinline__ int crow(int r, int hi) { return (r & 3) + 8 * (r >> 2) + 4 * hi; }
; __device__ __forceinline__ int v_st(int k, int c) { const int kk = (k & ~0xC) | ((k & 4) << 1) | ((k & 8) >> 1); return ((kk >> 3) * 4 + (c >> 5)) * 512 + ((kk & 7) * 32 + (c & 31)) * 2; }
; __device__ __forceinline__ int v_rd_base(int lane) { return ((lane & 3) << 3) | (((lane >> 2) & 3) << 6) | (((lane >> 4) & 1) << 5) | (((lane >> 5) & 1) << 8); }
; template <typename TQ>
; __device__ __forceinline__ void attn_dense_body(const TQ* __restrict__ Qb, const bf16* __restrict__ Kh, const bf16* __restrict__ Vh,
;                                                 bf16* __restrict__ Ob, int seq, char* lds) {
;     ...
;   const int tid = threadIdx.x, wid = tid >> 6, lane = tid & 63, r32 = lane & 31, hi = lane >> 5;
;   bf16* V_lds = (bf16*)lds; bf16* K_lds = (bf16*)(lds + 3 * SHM_V);
;   float* ws = (float*)(lds + 3 * SHM_V + 3 * SHM_K) + wid * 64; float* li_l = ws;
;     float l_reg = 0; f32x16 o[4] = {}; bf16x8 qr[8];
;   const TQ* Qw = Qb + (long)(wid * QBLK + r32) * LDQ + hi * 8;
; #pragma unroll
;   for (int d0 = 0; d0 < 8; ++d0) qr[d0] = SQ::tobf(SQ::ld8(Qw + d0 * 16));
;   const int sr = tid >> 4, sc = (tid & 15) * 8, vst0 = v_st(sr, sc), vst1 = v_st(32 + sr, sc);
;   const int vb0 = (int)(uintptr_t)V_lds + v_rd_base(lane);
;     ...
;   if (hi == 0) li_l[r32] = l_reg; asm volatile("s_waitcnt lgkmcnt(0)" ::: "memory");
;   float rli[16];
; #pragma unroll
;   for (int r = 0; r < 16; ++r) rli[r] = __builtin_amdgcn_rcpf(li_l[crow(r, hi)]);
;   bf16* Ow = Ob + (long)(wid * QBLK) * LDO;
.LBB0_1081:
	s_cmp_lt_i32 s30, 13
	s_cselect_b64 s[0:1], -1, 0
	s_cmp_gt_i32 s31, 12
	s_cselect_b64 s[4:5], -1, 0
	s_and_b64 s[0:1], s[0:1], s[4:5]
	s_andn2_b64 vcc, exec, s[0:1]
	s_cbranch_vccnz .LBB0_1154
	s_cmpk_gt_i32 s2, 0x3ff
	s_cbranch_scc1 .LBB0_1100
	s_add_u32 s3, s28, 0xf800000
	s_addc_u32 s38, s29, 0
	s_add_u32 s39, s28, 0x11800000
	s_addc_u32 s42, s29, 0
	s_waitcnt vmcnt(0)
	v_and_b32_e32 v3, 0x3c0, v160
	s_add_i32 s0, 0, 0x18000
	v_lshl_add_u32 v161, v3, 2, s0
	v_lshrrev_b32_e32 v3, 4, v160
	v_and_b32_e32 v8, 48, v3
	v_lshrrev_b32_e32 v9, 3, v160
	v_lshlrev_b32_e32 v6, 3, v160
	v_and_or_b32 v8, v3, 8, v8
	v_and_b32_e32 v7, 0x78, v6
	v_lshrrev_b32_e32 v9, 5, v160
	v_lshrrev_b32_e32 v8, 1, v8
	v_bfe_u32 v10, v6, 5, 2
	v_bfe_u32 v11, v160, 4, 2
	v_or_b32_e32 v8, v8, v10
	v_and_or_b32 v9, v3, 4, v11
	v_lshlrev_b32_e32 v11, 1, v7
	v_lshlrev_b32_e32 v8, 9, v8
	v_lshlrev_b32_e32 v9, 6, v9
	v_and_b32_e32 v12, 48, v11
	v_add_u32_e32 v13, 32, v3
	v_or3_b32 v177, v8, v9, v12
	v_and_b32_e32 v8, 0x70, v13
	v_lshlrev_b32_e32 v14, 1, v13
	v_and_or_b32 v8, v13, 8, v8
	v_lshrrev_b32_e32 v8, 1, v8
	v_or_b32_e32 v8, v8, v10
	v_lshlrev_b32_e32 v8, 9, v8
	v_or3_b32 v178, v8, v9, v12
	v_lshlrev_b32_e32 v9, 4, v160
	v_lshlrev_b32_e32 v10, 1, v160
	v_and_b32_e32 v8, 0xc0, v9
	v_and_b32_e32 v10, 32, v10
	v_and_b32_e32 v6, 0x118, v6
	s_cmp_lg_u32 0, -1
	s_waitcnt lgkmcnt(0)
	v_lshrrev_b32_e32 v1, 5, v176
	v_or3_b32 v6, v10, v8, v6
	s_cselect_b32 s0, 0, 0
	v_and_b32_e32 v0, 31, v160
	v_add_u32_e32 v179, s0, v6
	v_lshl_or_b32 v6, v3, 7, v7
	v_lshl_or_b32 v8, v13, 7, v7
	v_lshlrev_b32_e32 v3, 8, v3
	v_and_b32_e32 v7, 0xf0, v160
	v_lshlrev_b32_e32 v10, 8, v13
	v_lshlrev_b32_e32 v182, 4, v1
	v_bitop3_b32 v180, v11, v3, v7 bitop3:0xde
	v_bitop3_b32 v181, v11, v10, v7 bitop3:0xde
	v_lshlrev_b32_e32 v7, 8, v0
	v_and_b32_e32 v9, 0xf0, v9
	v_or_b32_e32 v11, 32, v182
	v_bitop3_b32 v184, v11, v7, v9 bitop3:0xde
	v_or_b32_e32 v11, 64, v182
	v_bitop3_b32 v185, v11, v7, v9 bitop3:0xde
	v_or_b32_e32 v11, 0x60, v182
	v_lshrrev_b32_e32 v2, 1, v160
	v_bitop3_b32 v186, v11, v7, v9 bitop3:0xde
	v_or_b32_e32 v11, 0x80, v182
	v_and_b32_e32 v5, 0x1e0, v2
	v_lshlrev_b32_e32 v4, 3, v1
	v_bitop3_b32 v187, v11, v7, v9 bitop3:0xde
	v_or_b32_e32 v11, 0xa0, v182
	v_lshlrev_b32_e32 v164, 13, v1
	v_and_b32_e32 v1, 15, v160
	v_or_b32_e32 v2, v5, v0
	v_mov_b32_e32 v163, 0
	v_bitop3_b32 v188, v11, v7, v9 bitop3:0xde
	v_or_b32_e32 v11, 0xc0, v182
	v_lshl_or_b32 v162, v1, 4, v3
	v_lshlrev_b32_e32 v2, 11, v2
	v_or_b32_e32 v10, 0x2000, v6
	v_add_u32_e32 v12, 0x3000, v6
	v_bitop3_b32 v183, v182, v7, v9 bitop3:0xde
	v_bitop3_b32 v189, v11, v7, v9 bitop3:0xde
	v_or_b32_e32 v11, 0xe0, v182
	v_or_b32_e32 v14, 0x4000, v6
	v_add_u32_e32 v16, 0x5000, v6
	v_lshlrev_b32_e32 v18, 10, v5
	v_lshl_add_u64 v[20:21], s[28:29], 0, v[162:163]
	s_mov_b64 s[6:7], 0x11812000
	s_mov_b32 s1, 0
	v_bitop3_b32 v190, v11, v7, v9 bitop3:0xde
	s_movk_i32 s43, 0x4000
	s_movk_i32 s44, 0x5000
	v_cmp_gt_u32_e64 s[4:5], 32, v176
	v_lshl_add_u32 v191, v0, 2, v161
	v_mov_b32_e32 v165, v163
	v_lshl_add_u64 v[166:167], v[20:21], 0, s[6:7]
	s_add_i32 s45, 0, 0x10000
	s_mov_b64 s[6:7], 0x8000
	v_lshlrev_b32_e32 v162, 1, v18
	v_lshlrev_b32_e32 v168, 1, v0
	s_movk_i32 s46, 0x1000
	s_mov_b32 s47, 0x8000
	s_mov_b32 s48, 0x9000
	s_mov_b32 s49, 0xc000
	s_mov_b32 s50, 0xd000
	v_lshlrev_b32_e32 v170, 1, v2
	v_mov_b32_e32 v171, v163
	v_lshlrev_b32_e32 v172, 1, v4
	v_mov_b32_e32 v173, v163
	v_lshlrev_b32_e32 v192, 1, v6
	v_lshlrev_b32_e32 v193, 1, v8
	v_add_u32_e32 v194, 0, v177
	v_add_u32_e32 v195, 0, v178
	v_add_u32_e32 v196, 0, v180
	v_add_u32_e32 v197, 0, v181
	v_lshlrev_b32_e32 v198, 1, v10
	v_lshlrev_b32_e32 v199, 1, v12
	v_add_u32_e32 v200, 0, v183
	v_add_u32_e32 v201, 0, v184
	v_add_u32_e32 v202, 0, v185
	v_add_u32_e32 v203, 0, v186
	v_add_u32_e32 v204, 0, v187
	v_lshlrev_b32_e32 v205, 1, v14
	v_lshlrev_b32_e32 v206, 1, v16
	s_mov_b32 s51, s2
	s_branch .LBB0_1085
.LBB0_1084:
	s_or_b64 exec, exec, s[14:15]
	s_waitcnt lgkmcnt(0)
	v_add_u32_e32 v72, v161, v182
	ds_read_b128 v[64:67], v72
	ds_read_b128 v[68:71], v72 offset:32
	ds_read_b128 v[76:79], v72 offset:64
	ds_read_b128 v[80:83], v72 offset:96
	s_lshl_b64 s[8:9], s[12:13], 11
	s_add_u32 s0, s36, s8
	s_addc_u32 s9, s37, s9
	s_lshl_b32 s8, s52, 1
	s_add_u32 s8, s0, s8
	s_addc_u32 s9, s9, 0
	v_lshrrev_b32_e32 v84, 5, v162
	v_add_u32_e32 v84, 0x19000, v84
	v_and_b32_e32 v85, 31, v176
	v_lshrrev_b32_e32 v86, 5, v176
	v_lshlrev_b32_e32 v85, 1, v85
	v_lshl_add_u32 v85, v86, 10, v85
	v_add_u32_e32 v85, v84, v85
	v_lshl_add_u32 v86, v176, 4, v84
	v_lshrrev_b32_e32 v87, 4, v176
	v_and_b32_e32 v88, 15, v176
	v_lshlrev_b32_e32 v88, 4, v88
	v_lshl_add_u32 v87, v87, 11, v88
	v_add_u32_e32 v87, v162, v87
	s_waitcnt lgkmcnt(2)
	v_rcp_f32_e32 v64, v64
	v_rcp_f32_e32 v65, v65
	v_rcp_f32_e32 v66, v66
	v_rcp_f32_e32 v67, v67
	v_rcp_f32_e32 v68, v68
	v_rcp_f32_e32 v69, v69
	v_rcp_f32_e32 v70, v70
	v_rcp_f32_e32 v71, v71
	s_waitcnt lgkmcnt(0)
; __device__ __forceinline__ int crow(int r, int hi) { return (r & 3) + 8 * (r >> 2) + 4 * hi; }
; template <typename TQ>
; __device__ __forceinline__ void attn_dense_body(const TQ* __restrict__ Qb, const bf16* __restrict__ Kh, const bf16* __restrict__ Vh,
;                                                 bf16* __restrict__ Ob, int seq, char* lds) {
;     ...
;   for (int r = 0; r < 16; ++r) rli[r] = __builtin_amdgcn_rcpf(li_l[crow(r, hi)]);
;   bf16* Ow = Ob + (long)(wid * QBLK) * LDO;
; #pragma unroll
;   for (int r = 0; r < 16; ++r) { int orow = crow(r, hi);
;     for (int d0 = 0; d0 < 4; ++d0) Ow[(long)orow * LDO + d0 * 32 + r32] = __float2bfloat16(o[d0][r] * rli[r]); }
	v_rcp_f32_e32 v76, v76
	v_rcp_f32_e32 v77, v77
	v_rcp_f32_e32 v78, v78
	v_rcp_f32_e32 v79, v79
	v_rcp_f32_e32 v80, v80
	v_rcp_f32_e32 v81, v81
	v_rcp_f32_e32 v82, v82
	v_rcp_f32_e32 v83, v83
	v_mul_f32_e32 v89, v0, v64
	v_mul_f32_e32 v90, v16, v64
	v_mul_f32_e32 v91, v32, v64
	v_mul_f32_e32 v92, v48, v64
	v_cvt_pk_bf16_f32 v93, v89, v90
	v_cvt_pk_bf16_f32 v94, v91, v92
	ds_write_b16 v85, v93 offset:0
	ds_write_b16_d16_hi v85, v93 offset:64
	ds_write_b16 v85, v94 offset:128
	ds_write_b16_d16_hi v85, v94 offset:192
	v_mul_f32_e32 v89, v1, v65
	v_mul_f32_e32 v90, v17, v65
	v_mul_f32_e32 v91, v33, v65
	v_mul_f32_e32 v92, v49, v65
	v_cvt_pk_bf16_f32 v93, v89, v90
	v_cvt_pk_bf16_f32 v94, v91, v92
	ds_write_b16 v85, v93 offset:256
	ds_write_b16_d16_hi v85, v93 offset:320
	ds_write_b16 v85, v94 offset:384
	ds_write_b16_d16_hi v85, v94 offset:448
	v_mul_f32_e32 v89, v2, v66
	v_mul_f32_e32 v90, v18, v66
	v_mul_f32_e32 v91, v34, v66
	v_mul_f32_e32 v92, v50, v66
	v_cvt_pk_bf16_f32 v93, v89, v90
	v_cvt_pk_bf16_f32 v94, v91, v92
	ds_write_b16 v85, v93 offset:512
	ds_write_b16_d16_hi v85, v93 offset:576
	ds_write_b16 v85, v94 offset:640
	ds_write_b16_d16_hi v85, v94 offset:704
	v_mul_f32_e32 v89, v3, v67
	v_mul_f32_e32 v90, v19, v67
	v_mul_f32_e32 v91, v35, v67
	v_mul_f32_e32 v92, v51, v67
	v_cvt_pk_bf16_f32 v93, v89, v90
	v_cvt_pk_bf16_f32 v94, v91, v92
	ds_write_b16 v85, v93 offset:768
	ds_write_b16_d16_hi v85, v93 offset:832
	ds_write_b16 v85, v94 offset:896
	ds_write_b16_d16_hi v85, v94 offset:960
	s_waitcnt lgkmcnt(0)
	ds_read_b128 v[96:99], v86
	ds_read_b128 v[100:103], v86 offset:1024
	s_add_u32 s60, s8, 0x0
	s_addc_u32 s61, s9, 0
	s_add_u32 s64, s8, 0x2000
	s_addc_u32 s65, s9, 0
	s_waitcnt lgkmcnt(1)
	global_store_dwordx4 v87, v[96:99], s[60:61]
	s_waitcnt lgkmcnt(0)
	global_store_dwordx4 v87, v[100:103], s[64:65]
	s_waitcnt lgkmcnt(0)
	v_mul_f32_e32 v89, v4, v68
	v_mul_f32_e32 v90, v20, v68
	v_mul_f32_e32 v91, v36, v68
	v_mul_f32_e32 v92, v52, v68
	v_cvt_pk_bf16_f32 v93, v89, v90
	v_cvt_pk_bf16_f32 v94, v91, v92
	ds_write_b16 v85, v93 offset:0
	ds_write_b16_d16_hi v85, v93 offset:64
	ds_write_b16 v85, v94 offset:128
	ds_write_b16_d16_hi v85, v94 offset:192
	v_mul_f32_e32 v89, v5, v69
	v_mul_f32_e32 v90, v21, v69
	v_mul_f32_e32 v91, v37, v69
	v_mul_f32_e32 v92, v53, v69
	v_cvt_pk_bf16_f32 v93, v89, v90
	v_cvt_pk_bf16_f32 v94, v91, v92
	ds_write_b16 v85, v93 offset:256
	ds_write_b16_d16_hi v85, v93 offset:320
	ds_write_b16 v85, v94 offset:384
	ds_write_b16_d16_hi v85, v94 offset:448
	v_mul_f32_e32 v89, v6, v70
	v_mul_f32_e32 v90, v22, v70
	v_mul_f32_e32 v91, v38, v70
	v_mul_f32_e32 v92, v54, v70
	v_cvt_pk_bf16_f32 v93, v89, v90
	v_cvt_pk_bf16_f32 v94, v91, v92
	ds_write_b16 v85, v93 offset:512
	ds_write_b16_d16_hi v85, v93 offset:576
	ds_write_b16 v85, v94 offset:640
	ds_write_b16_d16_hi v85, v94 offset:704
	v_mul_f32_e32 v89, v7, v71
	v_mul_f32_e32 v90, v23, v71
	v_mul_f32_e32 v91, v39, v71
	v_mul_f32_e32 v92, v55, v71
	v_cvt_pk_bf16_f32 v93, v89, v90
	v_cvt_pk_bf16_f32 v94, v91, v92
	ds_write_b16 v85, v93 offset:768
	ds_write_b16_d16_hi v85, v93 offset:832
	ds_write_b16 v85, v94 offset:896
	ds_write_b16_d16_hi v85, v94 offset:960
	s_waitcnt lgkmcnt(0)
	ds_read_b128 v[104:107], v86
	ds_read_b128 v[108:111], v86 offset:1024
	s_add_u32 s60, s8, 0x4000
	s_addc_u32 s61, s9, 0
	s_add_u32 s64, s8, 0x6000
	s_addc_u32 s65, s9, 0
	s_waitcnt lgkmcnt(1)
	global_store_dwordx4 v87, v[104:107], s[60:61]
	s_waitcnt lgkmcnt(0)
	global_store_dwordx4 v87, v[108:111], s[64:65]
	s_waitcnt lgkmcnt(0)
	v_mul_f32_e32 v89, v8, v76
	v_mul_f32_e32 v90, v24, v76
	v_mul_f32_e32 v91, v40, v76
	v_mul_f32_e32 v92, v56, v76
	v_cvt_pk_bf16_f32 v93, v89, v90
	v_cvt_pk_bf16_f32 v94, v91, v92
	ds_write_b16 v85, v93 offset:0
	ds_write_b16_d16_hi v85, v93 offset:64
	ds_write_b16 v85, v94 offset:128
	ds_write_b16_d16_hi v85, v94 offset:192
	v_mul_f32_e32 v89, v9, v77
	v_mul_f32_e32 v90, v25, v77
	v_mul_f32_e32 v91, v41, v77
	v_mul_f32_e32 v92, v57, v77
	v_cvt_pk_bf16_f32 v93, v89, v90
	v_cvt_pk_bf16_f32 v94, v91, v92
	ds_write_b16 v85, v93 offset:256
	ds_write_b16_d16_hi v85, v93 offset:320
	ds_write_b16 v85, v94 offset:384
	ds_write_b16_d16_hi v85, v94 offset:448
	v_mul_f32_e32 v89, v10, v78
	v_mul_f32_e32 v90, v26, v78
	v_mul_f32_e32 v91, v42, v78
	v_mul_f32_e32 v92, v58, v78
	v_cvt_pk_bf16_f32 v93, v89, v90
	v_cvt_pk_bf16_f32 v94, v91, v92
	ds_write_b16 v85, v93 offset:512
	ds_write_b16_d16_hi v85, v93 offset:576
	ds_write_b16 v85, v94 offset:640
	ds_write_b16_d16_hi v85, v94 offset:704
	v_mul_f32_e32 v89, v11, v79
	v_mul_f32_e32 v90, v27, v79
	v_mul_f32_e32 v91, v43, v79
	v_mul_f32_e32 v92, v59, v79
	v_cvt_pk_bf16_f32 v93, v89, v90
	v_cvt_pk_bf16_f32 v94, v91, v92
	ds_write_b16 v85, v93 offset:768
	ds_write_b16_d16_hi v85, v93 offset:832
	ds_write_b16 v85, v94 offset:896
	ds_write_b16_d16_hi v85, v94 offset:960
	s_waitcnt lgkmcnt(0)
	ds_read_b128 v[112:115], v86
	ds_read_b128 v[116:119], v86 offset:1024
	s_add_u32 s60, s8, 0x8000
	s_addc_u32 s61, s9, 0
	s_add_u32 s64, s8, 0xa000
	s_addc_u32 s65, s9, 0
	s_waitcnt lgkmcnt(1)
	global_store_dwordx4 v87, v[112:115], s[60:61]
	s_waitcnt lgkmcnt(0)
	global_store_dwordx4 v87, v[116:119], s[64:65]
	s_waitcnt lgkmcnt(0)
	v_mul_f32_e32 v89, v12, v80
	v_mul_f32_e32 v90, v28, v80
	v_mul_f32_e32 v91, v44, v80
	v_mul_f32_e32 v92, v60, v80
	v_cvt_pk_bf16_f32 v93, v89, v90
	v_cvt_pk_bf16_f32 v94, v91, v92
	ds_write_b16 v85, v93 offset:0
	ds_write_b16_d16_hi v85, v93 offset:64
	ds_write_b16 v85, v94 offset:128
	ds_write_b16_d16_hi v85, v94 offset:192
	v_mul_f32_e32 v89, v13, v81
	v_mul_f32_e32 v90, v29, v81
	v_mul_f32_e32 v91, v45, v81
	v_mul_f32_e32 v92, v61, v81
	v_cvt_pk_bf16_f32 v93, v89, v90
	v_cvt_pk_bf16_f32 v94, v91, v92
	ds_write_b16 v85, v93 offset:256
	ds_write_b16_d16_hi v85, v93 offset:320
	ds_write_b16 v85, v94 offset:384
	ds_write_b16_d16_hi v85, v94 offset:448
	v_mul_f32_e32 v89, v14, v82
	v_mul_f32_e32 v90, v30, v82
	v_mul_f32_e32 v91, v46, v82
	v_mul_f32_e32 v92, v62, v82
	v_cvt_pk_bf16_f32 v93, v89, v90
	v_cvt_pk_bf16_f32 v94, v91, v92
	ds_write_b16 v85, v93 offset:512
	ds_write_b16_d16_hi v85, v93 offset:576
	ds_write_b16 v85, v94 offset:640
	ds_write_b16_d16_hi v85, v94 offset:704
	v_mul_f32_e32 v89, v15, v83
	v_mul_f32_e32 v90, v31, v83
	v_mul_f32_e32 v91, v47, v83
	v_mul_f32_e32 v92, v63, v83
	v_cvt_pk_bf16_f32 v93, v89, v90
	v_cvt_pk_bf16_f32 v94, v91, v92
	ds_write_b16 v85, v93 offset:768
	ds_write_b16_d16_hi v85, v93 offset:832
	ds_write_b16 v85, v94 offset:896
	ds_write_b16_d16_hi v85, v94 offset:960
	s_waitcnt lgkmcnt(0)
	ds_read_b128 v[120:123], v86
	ds_read_b128 v[124:127], v86 offset:1024
	s_add_u32 s60, s8, 0xc000
	s_addc_u32 s61, s9, 0
	s_add_u32 s64, s8, 0xe000
	s_addc_u32 s65, s9, 0
	s_waitcnt lgkmcnt(1)
	global_store_dwordx4 v87, v[120:123], s[60:61]
	s_waitcnt lgkmcnt(0)
	global_store_dwordx4 v87, v[124:127], s[64:65]
	v_mov_b32_e32 v169, v163
	s_add_i32 s51, s51, s10
	s_cmpk_gt_i32 s51, 0x3ff
	s_waitcnt lgkmcnt(0)
	s_barrier
	s_cbranch_scc1 .LBB0_1100

; __device__ __forceinline__ void finishSM(f32x16& p0, f32x16& p1, float alpha, float& l_reg, bf16x8& pa0, bf16x8& pa1, bf16x8& pa2, bf16x8& pa3) {
;   for (int r = 0; r < 16; ++r) p1[r] = __builtin_amdgcn_exp2f(p1[r]);
;   float ps = 0; for (int r = 0; r < 16; ++r) ps += p0[r]; for (int r = 0; r < 16; ++r) ps += p1[r];
;   { auto rr = __builtin_amdgcn_permlane32_swap(__float_as_uint(ps), __float_as_uint(ps), false, false);
;     ps = __uint_as_float(rr[0]) + __uint_as_float(rr[1]); }
;   l_reg = l_reg * alpha + ps;
;     ...
;   PK4(p0, 0, pa0); PK4(p0, 8, pa1); PK4(p1, 0, pa2); PK4(p1, 8, pa3);
;     ...
; }
; __device__ __forceinline__ void qkt(f32x16& p0, f32x16& p1, const bf16* Ks, const bf16x8* qr, int r32, int hi) {
;   p0 = f32x16{}; p1 = f32x16{};
;   for (int d0 = 0; d0 < 8; ++d0) { int cb = (d0 * 16 + hi * 8) * 2;
;     bf16x8 b0 = *reinterpret_cast<const bf16x8*>((const char*)Ks + KSWZ(r32, cb));
;     bf16x8 b1 = *reinterpret_cast<const bf16x8*>((const char*)Ks + KSWZ(32 + r32, cb));
;     p0 = __builtin_amdgcn_mfma_f32_32x32x16_bf16(b0, qr[d0], p0, 0, 0, 0);
;     p1 = __builtin_amdgcn_mfma_f32_32x32x16_bf16(b1, qr[d0], p1, 0, 0, 0); }
; }
; __device__ __forceinline__ int v_st(int k, int c) { const int kk = (k & ~0xC) | ((k & 4) << 1) | ((k & 8) >> 1); return ((kk >> 3) * 4 + (c >> 5)) * 512 + ((kk & 7) * 32 + (c & 31)) * 2; }
; __device__ __forceinline__ int v_rd_base(int lane) { return ((lane & 3) << 3) | (((lane >> 2) & 3) << 6) | (((lane >> 4) & 1) << 5) | (((lane >> 5) & 1) << 8); }
; template <int OFF> __device__ __forceinline__ s16x4 tr_read(int vb) {
;   s16x4 r; asm volatile("ds_read_b64_tr_b16 %0, %1 offset:%2" : "=&v"(r) : "v"(vb), "i"(OFF) : "memory"); return r;
; }
; template <int D0> __device__ __forceinline__ void pv_one(f32x16& od, int vb, bf16x8 pa0, bf16x8 pa1, bf16x8 pa2, bf16x8 pa3) {
;   const s16x4 l0 = tr_read<v_rd_off(D0, 0, 0)>(vb), h0 = tr_read<v_rd_off(D0, 0, 1)>(vb), l1 = tr_read<v_rd_off(D0, 1, 0)>(vb), h1 = tr_read<v_rd_off(D0, 1, 1)>(vb);
;   const s16x4 l2 = tr_read<v_rd_off(D0, 2, 0)>(vb), h2 = tr_read<v_rd_off(D0, 2, 1)>(vb), l3 = tr_read<v_rd_off(D0, 3, 0)>(vb), h3 = tr_read<v_rd_off(D0, 3, 1)>(vb);
;   asm volatile("s_waitcnt lgkmcnt(0)" ::: "memory"); SBAR();
;     ...
;   od = __builtin_amdgcn_mfma_f32_32x32x16_bf16(pa0, PK(l0, h0), od, 0, 0, 0);
;   od = __builtin_amdgcn_mfma_f32_32x32x16_bf16(pa1, PK(l1, h1), od, 0, 0, 0);
.Latt_loop:
	s_mov_b32 s0, s54
	s_mov_b32 s54, s57
	s_lshl_b32 s19, s0, 14
	s_lshl_b32 s20, s54, 14
	s_lshl_b32 s18, s56, 14
	s_add_i32 s21, s18, 0
	v_add_u32_e32 v207, s20, v179
	s_waitcnt lgkmcnt(4)
	v_mfma_f32_32x32x16_bf16 v[96:111], v[208:211], v[140:143], 0
	v_exp_f32_e32 v64, v64
	v_exp_f32_e32 v65, v65
	v_cvt_pk_bf16_f32 v224, v224, v225
	v_mfma_f32_32x32x16_bf16 v[80:95], v[212:215], v[140:143], 0
	v_add_u32_e32 v248, s19, v186
	ds_read_b128 v[208:211], v248 offset:49152
	ds_read_b128 v[212:215], v248 offset:57344
	v_exp_f32_e32 v66, v66
	v_exp_f32_e32 v67, v67
	v_cvt_pk_bf16_f32 v225, v226, v227
	s_waitcnt lgkmcnt(4)
	v_mfma_f32_32x32x16_bf16 v[96:111], v[216:219], v[136:139], v[96:111]
	v_exp_f32_e32 v68, v68
	v_exp_f32_e32 v69, v69
	v_cvt_pk_bf16_f32 v226, v228, v229
	v_mfma_f32_32x32x16_bf16 v[80:95], v[220:223], v[136:139], v[80:95]
	v_add_u32_e32 v248, s19, v187
	ds_read_b128 v[216:219], v248 offset:49152
	ds_read_b128 v[220:223], v248 offset:57344
	v_exp_f32_e32 v70, v70
	v_exp_f32_e32 v71, v71
	v_cvt_pk_bf16_f32 v227, v230, v231
	v_add_f32_e32 v251, v64, v66
	s_waitcnt lgkmcnt(4)
	v_mfma_f32_32x32x16_bf16 v[96:111], v[240:243], v[132:135], v[96:111]
	v_exp_f32_e32 v72, v72
	v_exp_f32_e32 v73, v73
	v_add_f32_e32 v253, v65, v67
	v_mfma_f32_32x32x16_bf16 v[80:95], v[244:247], v[132:135], v[80:95]
	v_add_u32_e32 v248, s19, v188
	ds_read_b128 v[240:243], v248 offset:49152
	ds_read_b128 v[244:247], v248 offset:57344
	v_exp_f32_e32 v74, v74
	v_exp_f32_e32 v75, v75
	v_add_f32_e32 v251, v251, v68
	s_waitcnt lgkmcnt(4)
	v_mfma_f32_32x32x16_bf16 v[96:111], v[208:211], v[128:131], v[96:111]
	v_exp_f32_e32 v76, v76
	v_exp_f32_e32 v77, v77
	v_add_f32_e32 v253, v253, v69
	v_cvt_pk_bf16_f32 v228, v232, v233
	v_mfma_f32_32x32x16_bf16 v[80:95], v[212:215], v[128:131], v[80:95]
	v_add_u32_e32 v248, s19, v189
	ds_read_b128 v[208:211], v248 offset:49152
	ds_read_b128 v[212:215], v248 offset:57344
	v_exp_f32_e32 v78, v78
	v_exp_f32_e32 v79, v79
	v_add_f32_e32 v251, v251, v70
	v_cvt_pk_bf16_f32 v229, v234, v235
	s_waitcnt lgkmcnt(4)
	v_mfma_f32_32x32x16_bf16 v[96:111], v[216:219], v[124:127], v[96:111]
	v_add_f32_e32 v253, v253, v71
	v_cvt_pk_bf16_f32 v230, v236, v237
	v_cvt_pk_bf16_f32 v231, v238, v239
	v_add_f32_e32 v251, v251, v72
	v_mfma_f32_32x32x16_bf16 v[80:95], v[220:223], v[124:127], v[80:95]
	v_add_u32_e32 v248, s19, v190
	ds_read_b128 v[216:219], v248 offset:49152
	ds_read_b128 v[220:223], v248 offset:57344
	v_add_f32_e32 v253, v253, v73
	v_cvt_pk_bf16_f32 v232, v64, v65
	v_cvt_pk_bf16_f32 v233, v66, v67
	s_waitcnt lgkmcnt(4)
	v_mfma_f32_32x32x16_bf16 v[96:111], v[240:243], v[120:123], v[96:111]
	v_add_f32_e32 v251, v251, v74
	v_cvt_pk_bf16_f32 v234, v68, v69
	v_cvt_pk_bf16_f32 v235, v70, v71
	v_mfma_f32_32x32x16_bf16 v[80:95], v[244:247], v[120:123], v[80:95]
	ds_read_b64_tr_b16 v[240:241], v207 offset:0
	ds_read_b64_tr_b16 v[242:243], v207 offset:2048
	ds_read_b64_tr_b16 v[244:245], v207 offset:4096
	ds_read_b64_tr_b16 v[246:247], v207 offset:6144
	v_add_f32_e32 v253, v253, v75
	v_add_f32_e32 v251, v251, v76
	v_cvt_pk_bf16_f32 v236, v72, v73
	v_cvt_pk_bf16_f32 v237, v74, v75
	s_waitcnt lgkmcnt(6)
	v_mfma_f32_32x32x16_bf16 v[96:111], v[208:211], v[116:119], v[96:111]
	v_add_f32_e32 v253, v253, v77
	v_add_f32_e32 v251, v251, v78
	v_mfma_f32_32x32x16_bf16 v[80:95], v[212:215], v[116:119], v[80:95]
	ds_read_b64_tr_b16 v[208:209], v207 offset:8192
	ds_read_b64_tr_b16 v[210:211], v207 offset:10240
	ds_read_b64_tr_b16 v[212:213], v207 offset:12288
	ds_read_b64_tr_b16 v[214:215], v207 offset:14336
	v_add_f32_e32 v253, v253, v79
	v_cvt_pk_bf16_f32 v238, v76, v77
	v_cvt_pk_bf16_f32 v239, v78, v79
	s_waitcnt lgkmcnt(8)
	v_mfma_f32_32x32x16_bf16 v[96:111], v[216:219], v[112:115], v[96:111]
	v_add_f32_e32 v251, v251, v253
	v_add_f32_e32 v254, v254, v251
	v_mfma_f32_32x32x16_bf16 v[80:95], v[220:223], v[112:115], v[80:95]
	ds_read_b64_tr_b16 v[216:217], v207 offset:512
	ds_read_b64_tr_b16 v[218:219], v207 offset:2560
	ds_read_b64_tr_b16 v[220:221], v207 offset:4608
	ds_read_b64_tr_b16 v[222:223], v207 offset:6656
	v_add_f32_e32 v169, v169, v254
	s_waitcnt lgkmcnt(10)
	v_mfma_f32_32x32x16_bf16 v[0:15], v[224:227], v[240:243], v[0:15]
	ds_read_b64_tr_b16 v[64:65], v207 offset:8704
	ds_read_b64_tr_b16 v[66:67], v207 offset:10752
	s_waitcnt lgkmcnt(10)
	v_mfma_f32_32x32x16_bf16 v[0:15], v[228:231], v[244:247], v[0:15]
	ds_read_b64_tr_b16 v[68:69], v207 offset:12800
	ds_read_b64_tr_b16 v[70:71], v207 offset:14848
	v_exp_f32_e32 v96, v96
	v_exp_f32_e32 v97, v97
	s_waitcnt lgkmcnt(10)
	v_mfma_f32_32x32x16_bf16 v[0:15], v[232:235], v[208:211], v[0:15]
	ds_read_b64_tr_b16 v[72:73], v207 offset:1024
	ds_read_b64_tr_b16 v[74:75], v207 offset:3072
	v_exp_f32_e32 v98, v98
	v_exp_f32_e32 v99, v99
	s_waitcnt lgkmcnt(10)
	v_mfma_f32_32x32x16_bf16 v[0:15], v[236:239], v[212:215], v[0:15]
	ds_read_b64_tr_b16 v[76:77], v207 offset:5120
	ds_read_b64_tr_b16 v[78:79], v207 offset:7168
	v_exp_f32_e32 v100, v100
	v_exp_f32_e32 v101, v101
	v_add_f32_e32 v254, v96, v98
	s_waitcnt lgkmcnt(10)
	v_mfma_f32_32x32x16_bf16 v[16:31], v[224:227], v[216:219], v[16:31]
	ds_read_b64_tr_b16 v[240:241], v207 offset:9216
	ds_read_b64_tr_b16 v[242:243], v207 offset:11264
	v_exp_f32_e32 v102, v102
	v_exp_f32_e32 v103, v103
	v_add_f32_e32 v255, v97, v99
	s_waitcnt lgkmcnt(10)
	v_mfma_f32_32x32x16_bf16 v[16:31], v[228:231], v[220:223], v[16:31]
	ds_read_b64_tr_b16 v[244:245], v207 offset:13312
	ds_read_b64_tr_b16 v[246:247], v207 offset:15360
	v_exp_f32_e32 v104, v104
	v_exp_f32_e32 v105, v105
	v_add_f32_e32 v254, v254, v100
	s_waitcnt lgkmcnt(10)
; __device__ __forceinline__ void finishSM(f32x16& p0, f32x16& p1, float alpha, float& l_reg, bf16x8& pa0, bf16x8& pa1, bf16x8& pa2, bf16x8& pa3) {
;   for (int r = 0; r < 16; ++r) p1[r] = __builtin_amdgcn_exp2f(p1[r]);
;   float ps = 0; for (int r = 0; r < 16; ++r) ps += p0[r]; for (int r = 0; r < 16; ++r) ps += p1[r];
;   { auto rr = __builtin_amdgcn_permlane32_swap(__float_as_uint(ps), __float_as_uint(ps), false, false);
;     ps = __uint_as_float(rr[0]) + __uint_as_float(rr[1]); }
;   l_reg = l_reg * alpha + ps;
;     ...
;   PK4(p0, 0, pa0); PK4(p0, 8, pa1); PK4(p1, 0, pa2); PK4(p1, 8, pa3);
;     ...
; }
; __device__ __forceinline__ void qkt(f32x16& p0, f32x16& p1, const bf16* Ks, const bf16x8* qr, int r32, int hi) {
;   p0 = f32x16{}; p1 = f32x16{};
;   for (int d0 = 0; d0 < 8; ++d0) { int cb = (d0 * 16 + hi * 8) * 2;
;     bf16x8 b0 = *reinterpret_cast<const bf16x8*>((const char*)Ks + KSWZ(r32, cb));
;     bf16x8 b1 = *reinterpret_cast<const bf16x8*>((const char*)Ks + KSWZ(32 + r32, cb));
;     p0 = __builtin_amdgcn_mfma_f32_32x32x16_bf16(b0, qr[d0], p0, 0, 0, 0);
;     p1 = __builtin_amdgcn_mfma_f32_32x32x16_bf16(b1, qr[d0], p1, 0, 0, 0); }
; }
; __device__ __forceinline__ int v_st(int k, int c) { const int kk = (k & ~0xC) | ((k & 4) << 1) | ((k & 8) >> 1); return ((kk >> 3) * 4 + (c >> 5)) * 512 + ((kk & 7) * 32 + (c & 31)) * 2; }
; __device__ __forceinline__ int v_rd_base(int lane) { return ((lane & 3) << 3) | (((lane >> 2) & 3) << 6) | (((lane >> 4) & 1) << 5) | (((lane >> 5) & 1) << 8); }
; template <int OFF> __device__ __forceinline__ s16x4 tr_read(int vb) {
;   s16x4 r; asm volatile("ds_read_b64_tr_b16 %0, %1 offset:%2" : "=&v"(r) : "v"(vb), "i"(OFF) : "memory"); return r;
; }
; template <int D0> __device__ __forceinline__ void pv_one(f32x16& od, int vb, bf16x8 pa0, bf16x8 pa1, bf16x8 pa2, bf16x8 pa3) {
;   const s16x4 l0 = tr_read<v_rd_off(D0, 0, 0)>(vb), h0 = tr_read<v_rd_off(D0, 0, 1)>(vb), l1 = tr_read<v_rd_off(D0, 1, 0)>(vb), h1 = tr_read<v_rd_off(D0, 1, 1)>(vb);
;   const s16x4 l2 = tr_read<v_rd_off(D0, 2, 0)>(vb), h2 = tr_read<v_rd_off(D0, 2, 1)>(vb), l3 = tr_read<v_rd_off(D0, 3, 0)>(vb), h3 = tr_read<v_rd_off(D0, 3, 1)>(vb);
;   asm volatile("s_waitcnt lgkmcnt(0)" ::: "memory"); SBAR();
;     ...
;   od = __builtin_amdgcn_mfma_f32_32x32x16_bf16(pa0, PK(l0, h0), od, 0, 0, 0);
;   od = __builtin_amdgcn_mfma_f32_32x32x16_bf16(pa1, PK(l1, h1), od, 0, 0, 0);
	v_mfma_f32_32x32x16_bf16 v[16:31], v[232:235], v[64:67], v[16:31]
	ds_read_b64_tr_b16 v[64:65], v207 offset:1536
	ds_read_b64_tr_b16 v[66:67], v207 offset:3584
	v_exp_f32_e32 v106, v106
	v_exp_f32_e32 v107, v107
	v_add_f32_e32 v255, v255, v101
	s_waitcnt lgkmcnt(10)
	v_mfma_f32_32x32x16_bf16 v[16:31], v[236:239], v[68:71], v[16:31]
	ds_read_b64_tr_b16 v[68:69], v207 offset:5632
	ds_read_b64_tr_b16 v[70:71], v207 offset:7680
	v_exp_f32_e32 v108, v108
	v_exp_f32_e32 v109, v109
	v_add_f32_e32 v254, v254, v102
	v_add_u32_e32 v249, s21, v177
	s_waitcnt vmcnt(3)
	ds_write_b128 v249, v[144:147]
	s_waitcnt lgkmcnt(11)
	v_mfma_f32_32x32x16_bf16 v[32:47], v[224:227], v[72:75], v[32:47]
	ds_read_b64_tr_b16 v[72:73], v207 offset:9728
	ds_read_b64_tr_b16 v[74:75], v207 offset:11776
	v_exp_f32_e32 v110, v110
	v_exp_f32_e32 v111, v111
	v_add_f32_e32 v255, v255, v103
	v_add_u32_e32 v249, s21, v178
	s_waitcnt vmcnt(1)
	ds_write_b128 v249, v[148:151]
	s_waitcnt lgkmcnt(12)
	v_mfma_f32_32x32x16_bf16 v[32:47], v[228:231], v[76:79], v[32:47]
	ds_read_b64_tr_b16 v[76:77], v207 offset:13824
	ds_read_b64_tr_b16 v[78:79], v207 offset:15872
	v_add_f32_e32 v254, v254, v104
	v_add_f32_e32 v255, v255, v105
	v_add_f32_e32 v254, v254, v106
	v_add_u32_e32 v249, s21, v180
	ds_write_b128 v249, v[152:155] offset:49152
	s_waitcnt lgkmcnt(13)
	v_mfma_f32_32x32x16_bf16 v[32:47], v[232:235], v[240:243], v[32:47]
	v_add_f32_e32 v255, v255, v107
	v_add_f32_e32 v254, v254, v108
	v_add_f32_e32 v255, v255, v109
	v_add_u32_e32 v249, s21, v181
	s_waitcnt vmcnt(0)
	ds_write_b128 v249, v[156:159] offset:49152
	s_waitcnt lgkmcnt(12)
	v_mfma_f32_32x32x16_bf16 v[32:47], v[236:239], v[244:247], v[32:47]
	v_add_f32_e32 v254, v254, v110
	v_add_f32_e32 v255, v255, v111
	s_waitcnt lgkmcnt(0)
	s_barrier
	v_add_u32_e32 v248, s21, v183
	ds_read_b128 v[208:211], v248 offset:49152
	ds_read_b128 v[212:215], v248 offset:57344
	v_add_u32_e32 v248, s21, v184
	ds_read_b128 v[216:219], v248 offset:49152
	ds_read_b128 v[220:223], v248 offset:57344
	v_add_u32_e32 v248, s21, v185
	ds_read_b128 v[240:243], v248 offset:49152
	ds_read_b128 v[244:247], v248 offset:57344
	v_mfma_f32_32x32x16_bf16 v[48:63], v[224:227], v[64:67], v[48:63]
	v_add_f32_e32 v254, v254, v255
	v_mfma_f32_32x32x16_bf16 v[48:63], v[228:231], v[68:71], v[48:63]
	v_lshl_add_u64 v[144:145], v[174:175], 0, s[60:61]
	v_lshl_add_u64 v[148:149], v[174:175], 0, s[64:65]
	v_lshl_add_u64 v[152:153], v[174:175], 0, s[66:67]
	v_lshl_add_u64 v[156:157], v[174:175], 0, s[68:69]
	global_load_dwordx4 v[144:147], v[144:145], off
	global_load_dwordx4 v[148:151], v[148:149], off
	global_load_dwordx4 v[152:155], v[152:153], off
	global_load_dwordx4 v[156:159], v[156:157], off
	v_mfma_f32_32x32x16_bf16 v[48:63], v[232:235], v[72:75], v[48:63]
	v_mfma_f32_32x32x16_bf16 v[48:63], v[236:239], v[76:79], v[48:63]
	v_add_u32_e32 v250, s19, v179
	s_waitcnt lgkmcnt(4)
	v_mfma_f32_32x32x16_bf16 v[224:239], v[208:211], v[140:143], 0
	v_exp_f32_e32 v80, v80
	v_exp_f32_e32 v81, v81
	v_cvt_pk_bf16_f32 v96, v96, v97
	v_mfma_f32_32x32x16_bf16 v[64:79], v[212:215], v[140:143], 0
	v_add_u32_e32 v248, s21, v186
	ds_read_b128 v[208:211], v248 offset:49152
	ds_read_b128 v[212:215], v248 offset:57344
	v_exp_f32_e32 v82, v82
	v_exp_f32_e32 v83, v83
	v_cvt_pk_bf16_f32 v97, v98, v99
	s_waitcnt lgkmcnt(4)
	v_mfma_f32_32x32x16_bf16 v[224:239], v[216:219], v[136:139], v[224:239]
	v_exp_f32_e32 v84, v84
	v_exp_f32_e32 v85, v85
	v_cvt_pk_bf16_f32 v98, v100, v101
	v_mfma_f32_32x32x16_bf16 v[64:79], v[220:223], v[136:139], v[64:79]
	v_add_u32_e32 v248, s21, v187
	ds_read_b128 v[216:219], v248 offset:49152
	ds_read_b128 v[220:223], v248 offset:57344
	v_exp_f32_e32 v86, v86
	v_exp_f32_e32 v87, v87
	v_cvt_pk_bf16_f32 v99, v102, v103
	v_add_f32_e32 v251, v80, v82
	s_waitcnt lgkmcnt(4)
	v_mfma_f32_32x32x16_bf16 v[224:239], v[240:243], v[132:135], v[224:239]
	v_exp_f32_e32 v88, v88
	v_exp_f32_e32 v89, v89
	v_add_f32_e32 v253, v81, v83
	v_mfma_f32_32x32x16_bf16 v[64:79], v[244:247], v[132:135], v[64:79]
	v_add_u32_e32 v248, s21, v188
	ds_read_b128 v[240:243], v248 offset:49152
	ds_read_b128 v[244:247], v248 offset:57344
	v_exp_f32_e32 v90, v90
	v_exp_f32_e32 v91, v91
	v_add_f32_e32 v251, v251, v84
	s_waitcnt lgkmcnt(4)
	v_mfma_f32_32x32x16_bf16 v[224:239], v[208:211], v[128:131], v[224:239]
	v_exp_f32_e32 v92, v92
	v_exp_f32_e32 v93, v93
	v_add_f32_e32 v253, v253, v85
	v_cvt_pk_bf16_f32 v100, v104, v105
	v_mfma_f32_32x32x16_bf16 v[64:79], v[212:215], v[128:131], v[64:79]
	v_add_u32_e32 v248, s21, v189
	ds_read_b128 v[208:211], v248 offset:49152
	ds_read_b128 v[212:215], v248 offset:57344
	v_exp_f32_e32 v94, v94
	v_exp_f32_e32 v95, v95
	v_add_f32_e32 v251, v251, v86
	v_cvt_pk_bf16_f32 v101, v106, v107
	s_waitcnt lgkmcnt(4)
	v_mfma_f32_32x32x16_bf16 v[224:239], v[216:219], v[124:127], v[224:239]
	v_add_f32_e32 v253, v253, v87
	v_cvt_pk_bf16_f32 v102, v108, v109
	v_cvt_pk_bf16_f32 v103, v110, v111
	v_add_f32_e32 v251, v251, v88
	v_mfma_f32_32x32x16_bf16 v[64:79], v[220:223], v[124:127], v[64:79]
	v_add_u32_e32 v248, s21, v190
	ds_read_b128 v[216:219], v248 offset:49152
	ds_read_b128 v[220:223], v248 offset:57344
	v_add_f32_e32 v253, v253, v89
	v_cvt_pk_bf16_f32 v104, v80, v81
	v_cvt_pk_bf16_f32 v105, v82, v83
	s_waitcnt lgkmcnt(4)
; __device__ __forceinline__ void finishSM(f32x16& p0, f32x16& p1, float alpha, float& l_reg, bf16x8& pa0, bf16x8& pa1, bf16x8& pa2, bf16x8& pa3) {
;   for (int r = 0; r < 16; ++r) p1[r] = __builtin_amdgcn_exp2f(p1[r]);
;   float ps = 0; for (int r = 0; r < 16; ++r) ps += p0[r]; for (int r = 0; r < 16; ++r) ps += p1[r];
;   { auto rr = __builtin_amdgcn_permlane32_swap(__float_as_uint(ps), __float_as_uint(ps), false, false);
;     ps = __uint_as_float(rr[0]) + __uint_as_float(rr[1]); }
;   l_reg = l_reg * alpha + ps;
;     ...
;   PK4(p0, 0, pa0); PK4(p0, 8, pa1); PK4(p1, 0, pa2); PK4(p1, 8, pa3);
;     ...
; }
; __device__ __forceinline__ void qkt(f32x16& p0, f32x16& p1, const bf16* Ks, const bf16x8* qr, int r32, int hi) {
;   p0 = f32x16{}; p1 = f32x16{};
;   for (int d0 = 0; d0 < 8; ++d0) { int cb = (d0 * 16 + hi * 8) * 2;
;     bf16x8 b0 = *reinterpret_cast<const bf16x8*>((const char*)Ks + KSWZ(r32, cb));
;     bf16x8 b1 = *reinterpret_cast<const bf16x8*>((const char*)Ks + KSWZ(32 + r32, cb));
;     p0 = __builtin_amdgcn_mfma_f32_32x32x16_bf16(b0, qr[d0], p0, 0, 0, 0);
;     p1 = __builtin_amdgcn_mfma_f32_32x32x16_bf16(b1, qr[d0], p1, 0, 0, 0); }
; }
; __device__ __forceinline__ int v_st(int k, int c) { const int kk = (k & ~0xC) | ((k & 4) << 1) | ((k & 8) >> 1); return ((kk >> 3) * 4 + (c >> 5)) * 512 + ((kk & 7) * 32 + (c & 31)) * 2; }
; __device__ __forceinline__ int v_rd_base(int lane) { return ((lane & 3) << 3) | (((lane >> 2) & 3) << 6) | (((lane >> 4) & 1) << 5) | (((lane >> 5) & 1) << 8); }
; template <int OFF> __device__ __forceinline__ s16x4 tr_read(int vb) {
;   s16x4 r; asm volatile("ds_read_b64_tr_b16 %0, %1 offset:%2" : "=&v"(r) : "v"(vb), "i"(OFF) : "memory"); return r;
; }
; template <int D0> __device__ __forceinline__ void pv_one(f32x16& od, int vb, bf16x8 pa0, bf16x8 pa1, bf16x8 pa2, bf16x8 pa3) {
;   const s16x4 l0 = tr_read<v_rd_off(D0, 0, 0)>(vb), h0 = tr_read<v_rd_off(D0, 0, 1)>(vb), l1 = tr_read<v_rd_off(D0, 1, 0)>(vb), h1 = tr_read<v_rd_off(D0, 1, 1)>(vb);
;   const s16x4 l2 = tr_read<v_rd_off(D0, 2, 0)>(vb), h2 = tr_read<v_rd_off(D0, 2, 1)>(vb), l3 = tr_read<v_rd_off(D0, 3, 0)>(vb), h3 = tr_read<v_rd_off(D0, 3, 1)>(vb);
;   asm volatile("s_waitcnt lgkmcnt(0)" ::: "memory"); SBAR();
;     ...
;   od = __builtin_amdgcn_mfma_f32_32x32x16_bf16(pa0, PK(l0, h0), od, 0, 0, 0);
;   od = __builtin_amdgcn_mfma_f32_32x32x16_bf16(pa1, PK(l1, h1), od, 0, 0, 0);
	v_mfma_f32_32x32x16_bf16 v[224:239], v[240:243], v[120:123], v[224:239]
	v_add_f32_e32 v251, v251, v90
	v_cvt_pk_bf16_f32 v106, v84, v85
	v_cvt_pk_bf16_f32 v107, v86, v87
	v_mfma_f32_32x32x16_bf16 v[64:79], v[244:247], v[120:123], v[64:79]
	ds_read_b64_tr_b16 v[240:241], v250 offset:0
	ds_read_b64_tr_b16 v[242:243], v250 offset:2048
	ds_read_b64_tr_b16 v[244:245], v250 offset:4096
	ds_read_b64_tr_b16 v[246:247], v250 offset:6144
	v_add_f32_e32 v253, v253, v91
	v_add_f32_e32 v251, v251, v92
	v_cvt_pk_bf16_f32 v108, v88, v89
	v_cvt_pk_bf16_f32 v109, v90, v91
	s_waitcnt lgkmcnt(6)
	v_mfma_f32_32x32x16_bf16 v[224:239], v[208:211], v[116:119], v[224:239]
	v_add_f32_e32 v253, v253, v93
	v_add_f32_e32 v251, v251, v94
	v_mfma_f32_32x32x16_bf16 v[64:79], v[212:215], v[116:119], v[64:79]
	ds_read_b64_tr_b16 v[208:209], v250 offset:8192
	ds_read_b64_tr_b16 v[210:211], v250 offset:10240
	ds_read_b64_tr_b16 v[212:213], v250 offset:12288
	ds_read_b64_tr_b16 v[214:215], v250 offset:14336
	v_add_f32_e32 v253, v253, v95
	v_cvt_pk_bf16_f32 v110, v92, v93
	v_cvt_pk_bf16_f32 v111, v94, v95
	s_waitcnt lgkmcnt(8)
	v_mfma_f32_32x32x16_bf16 v[224:239], v[216:219], v[112:115], v[224:239]
	v_add_f32_e32 v251, v251, v253
	v_add_f32_e32 v254, v254, v251
	v_mfma_f32_32x32x16_bf16 v[64:79], v[220:223], v[112:115], v[64:79]
	ds_read_b64_tr_b16 v[216:217], v250 offset:512
	ds_read_b64_tr_b16 v[218:219], v250 offset:2560
	ds_read_b64_tr_b16 v[220:221], v250 offset:4608
	ds_read_b64_tr_b16 v[222:223], v250 offset:6656
	v_add_f32_e32 v169, v169, v254
	s_waitcnt lgkmcnt(10)
	v_mfma_f32_32x32x16_bf16 v[0:15], v[96:99], v[240:243], v[0:15]
	ds_read_b64_tr_b16 v[80:81], v250 offset:8704
	ds_read_b64_tr_b16 v[82:83], v250 offset:10752
	s_waitcnt lgkmcnt(10)
	v_mfma_f32_32x32x16_bf16 v[0:15], v[100:103], v[244:247], v[0:15]
	ds_read_b64_tr_b16 v[84:85], v250 offset:12800
	ds_read_b64_tr_b16 v[86:87], v250 offset:14848
	v_exp_f32_e32 v224, v224
	v_exp_f32_e32 v225, v225
	s_waitcnt lgkmcnt(10)
	v_mfma_f32_32x32x16_bf16 v[0:15], v[104:107], v[208:211], v[0:15]
	ds_read_b64_tr_b16 v[88:89], v250 offset:1024
	ds_read_b64_tr_b16 v[90:91], v250 offset:3072
	v_exp_f32_e32 v226, v226
	v_exp_f32_e32 v227, v227
	s_waitcnt lgkmcnt(10)
	v_mfma_f32_32x32x16_bf16 v[0:15], v[108:111], v[212:215], v[0:15]
	ds_read_b64_tr_b16 v[92:93], v250 offset:5120
	ds_read_b64_tr_b16 v[94:95], v250 offset:7168
	v_exp_f32_e32 v228, v228
	v_exp_f32_e32 v229, v229
	v_add_f32_e32 v254, v224, v226
	s_waitcnt lgkmcnt(10)
	v_mfma_f32_32x32x16_bf16 v[16:31], v[96:99], v[216:219], v[16:31]
	ds_read_b64_tr_b16 v[240:241], v250 offset:9216
	ds_read_b64_tr_b16 v[242:243], v250 offset:11264
	v_exp_f32_e32 v230, v230
	v_exp_f32_e32 v231, v231
	v_add_f32_e32 v255, v225, v227
	s_waitcnt lgkmcnt(10)
	v_mfma_f32_32x32x16_bf16 v[16:31], v[100:103], v[220:223], v[16:31]
	ds_read_b64_tr_b16 v[244:245], v250 offset:13312
	ds_read_b64_tr_b16 v[246:247], v250 offset:15360
	v_exp_f32_e32 v232, v232
	v_exp_f32_e32 v233, v233
	v_add_f32_e32 v254, v254, v228
	s_waitcnt lgkmcnt(10)
	v_mfma_f32_32x32x16_bf16 v[16:31], v[104:107], v[80:83], v[16:31]
	ds_read_b64_tr_b16 v[80:81], v250 offset:1536
	ds_read_b64_tr_b16 v[82:83], v250 offset:3584
	v_exp_f32_e32 v234, v234
	v_exp_f32_e32 v235, v235
	v_add_f32_e32 v255, v255, v229
	s_waitcnt lgkmcnt(10)
	v_mfma_f32_32x32x16_bf16 v[16:31], v[108:111], v[84:87], v[16:31]
	ds_read_b64_tr_b16 v[84:85], v250 offset:5632
	ds_read_b64_tr_b16 v[86:87], v250 offset:7680
	v_exp_f32_e32 v236, v236
	v_exp_f32_e32 v237, v237
	v_add_f32_e32 v254, v254, v230
	v_add_u32_e32 v249, s20, v177
	s_waitcnt vmcnt(3)
	ds_write_b128 v249, v[144:147]
	s_waitcnt lgkmcnt(11)
	v_mfma_f32_32x32x16_bf16 v[32:47], v[96:99], v[88:91], v[32:47]
	ds_read_b64_tr_b16 v[88:89], v250 offset:9728
	ds_read_b64_tr_b16 v[90:91], v250 offset:11776
	v_exp_f32_e32 v238, v238
	v_exp_f32_e32 v239, v239
	v_add_f32_e32 v255, v255, v231
	v_add_u32_e32 v249, s20, v178
	s_waitcnt vmcnt(2)
	ds_write_b128 v249, v[148:151]
	s_waitcnt lgkmcnt(12)
	v_mfma_f32_32x32x16_bf16 v[32:47], v[100:103], v[92:95], v[32:47]
	ds_read_b64_tr_b16 v[92:93], v250 offset:13824
	ds_read_b64_tr_b16 v[94:95], v250 offset:15872
	v_add_f32_e32 v254, v254, v232
	v_add_f32_e32 v255, v255, v233
	v_add_f32_e32 v254, v254, v234
	v_add_u32_e32 v249, s20, v180
	s_waitcnt vmcnt(1)
	ds_write_b128 v249, v[152:155] offset:49152
	s_waitcnt lgkmcnt(13)
	v_mfma_f32_32x32x16_bf16 v[32:47], v[104:107], v[240:243], v[32:47]
	v_add_f32_e32 v255, v255, v235
	v_add_f32_e32 v254, v254, v236
	v_add_f32_e32 v255, v255, v237
	v_add_u32_e32 v249, s20, v181
	s_waitcnt vmcnt(0)
	ds_write_b128 v249, v[156:159] offset:49152
	s_waitcnt lgkmcnt(12)
	v_mfma_f32_32x32x16_bf16 v[32:47], v[108:111], v[244:247], v[32:47]
	v_add_f32_e32 v254, v254, v238
	v_add_f32_e32 v255, v255, v239
	s_waitcnt lgkmcnt(0)
	s_barrier
	v_add_u32_e32 v248, s20, v183
	ds_read_b128 v[208:211], v248 offset:49152
	ds_read_b128 v[212:215], v248 offset:57344
	v_add_u32_e32 v248, s20, v184
	ds_read_b128 v[216:219], v248 offset:49152
	ds_read_b128 v[220:223], v248 offset:57344
	v_add_u32_e32 v248, s20, v185
	ds_read_b128 v[240:243], v248 offset:49152
	ds_read_b128 v[244:247], v248 offset:57344
	v_mfma_f32_32x32x16_bf16 v[48:63], v[96:99], v[80:83], v[48:63]
	v_add_f32_e32 v254, v254, v255
	v_mfma_f32_32x32x16_bf16 v[48:63], v[100:103], v[84:87], v[48:63]
	s_cmp_ge_u32 s55, s53
	s_cbranch_scc1 .Latt_noload
	v_lshl_add_u64 v[144:145], v[174:175], 0, s[70:71]
	v_lshl_add_u64 v[152:153], v[174:175], 0, s[76:77]
	v_lshl_add_u64 v[156:157], v[174:175], 0, s[78:79]
	global_load_dwordx4 v[144:147], v[144:145], off
	global_load_dwordx4 v[152:155], v[152:153], off
	global_load_dwordx4 v[148:151], v[174:175], off
	global_load_dwordx4 v[156:159], v[156:157], off

; __device__ __forceinline__ void finishSM(f32x16& p0, f32x16& p1, float alpha, float& l_reg, bf16x8& pa0, bf16x8& pa1, bf16x8& pa2, bf16x8& pa3) {
;   for (int r = 0; r < 16; ++r) p1[r] = __builtin_amdgcn_exp2f(p1[r]);
;   float ps = 0; for (int r = 0; r < 16; ++r) ps += p0[r]; for (int r = 0; r < 16; ++r) ps += p1[r];
;   { auto rr = __builtin_amdgcn_permlane32_swap(__float_as_uint(ps), __float_as_uint(ps), false, false);
;     ps = __uint_as_float(rr[0]) + __uint_as_float(rr[1]); }
;   l_reg = l_reg * alpha + ps;
;     ...
;   PK4(p0, 0, pa0); PK4(p0, 8, pa1); PK4(p1, 0, pa2); PK4(p1, 8, pa3);
;     ...
; }
; __device__ __forceinline__ void qkt(f32x16& p0, f32x16& p1, const bf16* Ks, const bf16x8* qr, int r32, int hi) {
;   p0 = f32x16{}; p1 = f32x16{};
;   for (int d0 = 0; d0 < 8; ++d0) { int cb = (d0 * 16 + hi * 8) * 2;
;     bf16x8 b0 = *reinterpret_cast<const bf16x8*>((const char*)Ks + KSWZ(r32, cb));
;     bf16x8 b1 = *reinterpret_cast<const bf16x8*>((const char*)Ks + KSWZ(32 + r32, cb));
;     p0 = __builtin_amdgcn_mfma_f32_32x32x16_bf16(b0, qr[d0], p0, 0, 0, 0);
;     p1 = __builtin_amdgcn_mfma_f32_32x32x16_bf16(b1, qr[d0], p1, 0, 0, 0); }
; }
; __device__ __forceinline__ int v_st(int k, int c) { const int kk = (k & ~0xC) | ((k & 4) << 1) | ((k & 8) >> 1); return ((kk >> 3) * 4 + (c >> 5)) * 512 + ((kk & 7) * 32 + (c & 31)) * 2; }
; __device__ __forceinline__ int v_rd_base(int lane) { return ((lane & 3) << 3) | (((lane >> 2) & 3) << 6) | (((lane >> 4) & 1) << 5) | (((lane >> 5) & 1) << 8); }
; template <int OFF> __device__ __forceinline__ s16x4 tr_read(int vb) {
;   s16x4 r; asm volatile("ds_read_b64_tr_b16 %0, %1 offset:%2" : "=&v"(r) : "v"(vb), "i"(OFF) : "memory"); return r;
; }
; template <int D0> __device__ __forceinline__ void pv_one(f32x16& od, int vb, bf16x8 pa0, bf16x8 pa1, bf16x8 pa2, bf16x8 pa3) {
;   const s16x4 l0 = tr_read<v_rd_off(D0, 0, 0)>(vb), h0 = tr_read<v_rd_off(D0, 0, 1)>(vb), l1 = tr_read<v_rd_off(D0, 1, 0)>(vb), h1 = tr_read<v_rd_off(D0, 1, 1)>(vb);
;   const s16x4 l2 = tr_read<v_rd_off(D0, 2, 0)>(vb), h2 = tr_read<v_rd_off(D0, 2, 1)>(vb), l3 = tr_read<v_rd_off(D0, 3, 0)>(vb), h3 = tr_read<v_rd_off(D0, 3, 1)>(vb);
;   asm volatile("s_waitcnt lgkmcnt(0)" ::: "memory"); SBAR();
;     ...
;   od = __builtin_amdgcn_mfma_f32_32x32x16_bf16(pa0, PK(l0, h0), od, 0, 0, 0);
;   od = __builtin_amdgcn_mfma_f32_32x32x16_bf16(pa1, PK(l1, h1), od, 0, 0, 0);
.LBB0_1098:
	s_add_i32 s0, s20, 0
	v_add_u32_e32 v84, s0, v183
	ds_read_b128 v[80:83], v84 offset:49152
	ds_read_b128 v[84:87], v84 offset:57344
	s_waitcnt vmcnt(1)
	v_add_u32_e32 v152, s0, v185
	v_add_u32_e32 v174, s0, v186
	v_add_u32_e32 v175, s0, v187
	s_waitcnt lgkmcnt(1)
	v_mfma_f32_32x32x16_bf16 v[96:111], v[80:83], v[140:143], 0
	v_add_u32_e32 v80, s0, v184
	ds_read_b128 v[144:147], v80 offset:49152
	ds_read_b128 v[148:151], v80 offset:57344
	v_exp_f32_e32 v65, v65
	v_exp_f32_e32 v67, v67
	v_exp_f32_e32 v208, v68
	v_exp_f32_e32 v210, v73
	v_exp_f32_e32 v250, v74
	s_waitcnt lgkmcnt(2)
	v_mfma_f32_32x32x16_bf16 v[80:95], v[84:87], v[140:143], 0
	ds_read_b128 v[140:143], v152 offset:49152
	ds_read_b128 v[152:155], v152 offset:57344
	s_waitcnt vmcnt(0)
	ds_read_b128 v[156:159], v174 offset:49152
	ds_read_b128 v[226:229], v174 offset:57344
	ds_read_b128 v[230:233], v175 offset:49152
	ds_read_b128 v[234:237], v175 offset:57344
	v_add_u32_e32 v174, s0, v188
	v_exp_f32_e32 v175, v66
	v_exp_f32_e32 v251, v75
	s_waitcnt lgkmcnt(7)
	v_mfma_f32_32x32x16_bf16 v[96:111], v[144:147], v[136:139], v[96:111]
	ds_read_b128 v[144:147], v174 offset:49152
	ds_read_b128 v[238:241], v174 offset:57344
	v_add_u32_e32 v174, s0, v189
	ds_read_b128 v[242:245], v174 offset:49152
	ds_read_b128 v[246:249], v174 offset:57344
	v_add_u32_e32 v174, s0, v190
	s_waitcnt lgkmcnt(10)
	v_mfma_f32_32x32x16_bf16 v[80:95], v[148:151], v[136:139], v[80:95]
	ds_read_b128 v[136:139], v174 offset:49152
	ds_read_b128 v[148:151], v174 offset:57344
	v_exp_f32_e32 v174, v64
	v_add_f32_e32 v64, 0, v223
	v_add_f32_e32 v64, v225, v64
	v_add_f32_e32 v64, v221, v64
	v_add_f32_e32 v64, v224, v64
	v_add_f32_e32 v64, v220, v64
	s_waitcnt lgkmcnt(11)
	v_mfma_f32_32x32x16_bf16 v[96:111], v[140:143], v[132:135], v[96:111]
	v_add_f32_e32 v64, v222, v64
	v_add_f32_e32 v64, v218, v64
	v_add_f32_e32 v64, v219, v64
	v_add_f32_e32 v64, v215, v64
	v_add_f32_e32 v64, v217, v64
	v_add_f32_e32 v64, v214, v64
	v_add_f32_e32 v64, v216, v64
	s_waitcnt lgkmcnt(10)
	v_mfma_f32_32x32x16_bf16 v[80:95], v[152:155], v[132:135], v[80:95]
	v_add_f32_e32 v64, v211, v64
	v_add_f32_e32 v64, v213, v64
	v_add_f32_e32 v64, v209, v64
	v_add_f32_e32 v64, v212, v64
	v_add_f32_e32 v64, v174, v64
	v_exp_f32_e32 v140, v69
	v_add_f32_e32 v64, v65, v64
	s_waitcnt lgkmcnt(9)
	v_mfma_f32_32x32x16_bf16 v[96:111], v[156:159], v[128:131], v[96:111]
	v_exp_f32_e32 v141, v70
	v_add_f32_e32 v64, v175, v64
	v_exp_f32_e32 v142, v71
	v_add_f32_e32 v64, v67, v64
	v_exp_f32_e32 v143, v72
	v_add_f32_e32 v64, v208, v64
	v_add_f32_e32 v64, v140, v64
	s_waitcnt lgkmcnt(8)
	v_mfma_f32_32x32x16_bf16 v[80:95], v[226:229], v[128:131], v[80:95]
	v_add_f32_e32 v64, v141, v64
	v_add_f32_e32 v64, v142, v64
	v_exp_f32_e32 v132, v76
	v_add_f32_e32 v64, v143, v64
	v_exp_f32_e32 v133, v77
	v_add_f32_e32 v64, v210, v64
	v_exp_f32_e32 v134, v78
	s_waitcnt lgkmcnt(7)
	v_mfma_f32_32x32x16_bf16 v[96:111], v[230:233], v[124:127], v[96:111]
	v_add_f32_e32 v64, v250, v64
	v_exp_f32_e32 v135, v79
	v_add_f32_e32 v64, v251, v64
	v_add_f32_e32 v64, v132, v64
	v_add_f32_e32 v64, v133, v64
	v_add_f32_e32 v64, v134, v64
	v_add_f32_e32 v64, v135, v64
	s_waitcnt lgkmcnt(6)
	v_mfma_f32_32x32x16_bf16 v[80:95], v[234:237], v[124:127], v[80:95]
	v_mov_b32_e32 v66, v64
	s_nop 1
	v_permlane32_swap_b32_e32 v64, v66
	v_cvt_pk_bf16_f32 v68, v223, v225
	v_cvt_pk_bf16_f32 v69, v221, v224
	v_cvt_pk_bf16_f32 v70, v220, v222
	v_cvt_pk_bf16_f32 v71, v218, v219
	s_waitcnt lgkmcnt(5)
	v_mfma_f32_32x32x16_bf16 v[96:111], v[144:147], v[120:123], v[96:111]
	v_cvt_pk_bf16_f32 v72, v215, v217
	v_cvt_pk_bf16_f32 v73, v214, v216
	v_cvt_pk_bf16_f32 v74, v211, v213
	v_cvt_pk_bf16_f32 v75, v209, v212
	v_cvt_pk_bf16_f32 v76, v174, v65
	v_cvt_pk_bf16_f32 v77, v175, v67
	v_cvt_pk_bf16_f32 v78, v208, v140
	s_waitcnt lgkmcnt(4)
	v_mfma_f32_32x32x16_bf16 v[80:95], v[238:241], v[120:123], v[80:95]
	v_cvt_pk_bf16_f32 v79, v141, v142
	s_waitcnt lgkmcnt(3)
	v_mfma_f32_32x32x16_bf16 v[96:111], v[242:245], v[116:119], v[96:111]
	s_waitcnt lgkmcnt(2)
	v_mfma_f32_32x32x16_bf16 v[80:95], v[246:249], v[116:119], v[80:95]
	v_cvt_pk_bf16_f32 v116, v143, v210
	v_cvt_pk_bf16_f32 v117, v250, v251
	v_cvt_pk_bf16_f32 v118, v132, v133
	v_cvt_pk_bf16_f32 v119, v134, v135
	s_nop 0
	s_waitcnt lgkmcnt(1)
	v_mfma_f32_32x32x16_bf16 v[96:111], v[136:139], v[112:115], v[96:111]
	s_waitcnt lgkmcnt(0)
	v_mfma_f32_32x32x16_bf16 v[80:95], v[148:151], v[112:115], v[80:95]
	v_add_u32_e32 v65, s18, v179
	ds_read_b64_tr_b16 v[112:113], v65 offset:0
	ds_read_b64_tr_b16 v[114:115], v65 offset:0x800
	ds_read_b64_tr_b16 v[120:121], v65 offset:0x1000
	ds_read_b64_tr_b16 v[122:123], v65 offset:0x1800
	ds_read_b64_tr_b16 v[124:125], v65 offset:0x2000
	ds_read_b64_tr_b16 v[126:127], v65 offset:0x2800
	ds_read_b64_tr_b16 v[128:129], v65 offset:0x3000
	ds_read_b64_tr_b16 v[130:131], v65 offset:0x3800
	s_waitcnt lgkmcnt(0)
	s_nop 0
	v_mfma_f32_32x32x16_bf16 v[0:15], v[68:71], v[112:115], v[0:15]
	ds_read_b64_tr_b16 v[112:113], v65 offset:0x200
	ds_read_b64_tr_b16 v[114:115], v65 offset:0xa00
	v_mfma_f32_32x32x16_bf16 v[0:15], v[72:75], v[120:123], v[0:15]
	ds_read_b64_tr_b16 v[120:121], v65 offset:0x1200
	ds_read_b64_tr_b16 v[122:123], v65 offset:0x1a00
	v_mfma_f32_32x32x16_bf16 v[0:15], v[76:79], v[124:127], v[0:15]
	ds_read_b64_tr_b16 v[124:125], v65 offset:0x2200
	ds_read_b64_tr_b16 v[126:127], v65 offset:0x2a00
	ds_read_b64_tr_b16 v[132:133], v65 offset:0x3200
	ds_read_b64_tr_b16 v[134:135], v65 offset:0x3a00
	s_waitcnt lgkmcnt(0)
; __device__ __forceinline__ void finishSM(f32x16& p0, f32x16& p1, float alpha, float& l_reg, bf16x8& pa0, bf16x8& pa1, bf16x8& pa2, bf16x8& pa3) {
;   for (int r = 0; r < 16; ++r) p1[r] = __builtin_amdgcn_exp2f(p1[r]);
;   float ps = 0; for (int r = 0; r < 16; ++r) ps += p0[r]; for (int r = 0; r < 16; ++r) ps += p1[r];
;   { auto rr = __builtin_amdgcn_permlane32_swap(__float_as_uint(ps), __float_as_uint(ps), false, false);
;     ps = __uint_as_float(rr[0]) + __uint_as_float(rr[1]); }
;   l_reg = l_reg * alpha + ps;
;     ...
;   PK4(p0, 0, pa0); PK4(p0, 8, pa1); PK4(p1, 0, pa2); PK4(p1, 8, pa3);
;     ...
; }
; __device__ __forceinline__ void qkt(f32x16& p0, f32x16& p1, const bf16* Ks, const bf16x8* qr, int r32, int hi) {
;   p0 = f32x16{}; p1 = f32x16{};
;   for (int d0 = 0; d0 < 8; ++d0) { int cb = (d0 * 16 + hi * 8) * 2;
;     bf16x8 b0 = *reinterpret_cast<const bf16x8*>((const char*)Ks + KSWZ(r32, cb));
;     bf16x8 b1 = *reinterpret_cast<const bf16x8*>((const char*)Ks + KSWZ(32 + r32, cb));
;     p0 = __builtin_amdgcn_mfma_f32_32x32x16_bf16(b0, qr[d0], p0, 0, 0, 0);
;     p1 = __builtin_amdgcn_mfma_f32_32x32x16_bf16(b1, qr[d0], p1, 0, 0, 0); }
; }
; __device__ __forceinline__ int v_st(int k, int c) { const int kk = (k & ~0xC) | ((k & 4) << 1) | ((k & 8) >> 1); return ((kk >> 3) * 4 + (c >> 5)) * 512 + ((kk & 7) * 32 + (c & 31)) * 2; }
; __device__ __forceinline__ int v_rd_base(int lane) { return ((lane & 3) << 3) | (((lane >> 2) & 3) << 6) | (((lane >> 4) & 1) << 5) | (((lane >> 5) & 1) << 8); }
; template <int OFF> __device__ __forceinline__ s16x4 tr_read(int vb) {
;   s16x4 r; asm volatile("ds_read_b64_tr_b16 %0, %1 offset:%2" : "=&v"(r) : "v"(vb), "i"(OFF) : "memory"); return r;
; }
; template <int D0> __device__ __forceinline__ void pv_one(f32x16& od, int vb, bf16x8 pa0, bf16x8 pa1, bf16x8 pa2, bf16x8 pa3) {
;   const s16x4 l0 = tr_read<v_rd_off(D0, 0, 0)>(vb), h0 = tr_read<v_rd_off(D0, 0, 1)>(vb), l1 = tr_read<v_rd_off(D0, 1, 0)>(vb), h1 = tr_read<v_rd_off(D0, 1, 1)>(vb);
;   const s16x4 l2 = tr_read<v_rd_off(D0, 2, 0)>(vb), h2 = tr_read<v_rd_off(D0, 2, 1)>(vb), l3 = tr_read<v_rd_off(D0, 3, 0)>(vb), h3 = tr_read<v_rd_off(D0, 3, 1)>(vb);
;   asm volatile("s_waitcnt lgkmcnt(0)" ::: "memory"); SBAR();
;     ...
;   od = __builtin_amdgcn_mfma_f32_32x32x16_bf16(pa0, PK(l0, h0), od, 0, 0, 0);
;   od = __builtin_amdgcn_mfma_f32_32x32x16_bf16(pa1, PK(l1, h1), od, 0, 0, 0);
	v_mfma_f32_32x32x16_bf16 v[0:15], v[116:119], v[128:131], v[0:15]
	v_mfma_f32_32x32x16_bf16 v[16:31], v[68:71], v[112:115], v[16:31]
	ds_read_b64_tr_b16 v[112:113], v65 offset:0x400
	ds_read_b64_tr_b16 v[114:115], v65 offset:0xc00
	v_mfma_f32_32x32x16_bf16 v[16:31], v[72:75], v[120:123], v[16:31]
	ds_read_b64_tr_b16 v[120:121], v65 offset:0x1400
	ds_read_b64_tr_b16 v[122:123], v65 offset:0x1c00
	v_mfma_f32_32x32x16_bf16 v[16:31], v[76:79], v[124:127], v[16:31]
	ds_read_b64_tr_b16 v[124:125], v65 offset:0x2400
	ds_read_b64_tr_b16 v[126:127], v65 offset:0x2c00
	ds_read_b64_tr_b16 v[128:129], v65 offset:0x3400
	ds_read_b64_tr_b16 v[130:131], v65 offset:0x3c00
	s_waitcnt lgkmcnt(0)
	v_mfma_f32_32x32x16_bf16 v[16:31], v[116:119], v[132:135], v[16:31]
	v_mfma_f32_32x32x16_bf16 v[32:47], v[68:71], v[112:115], v[32:47]
	ds_read_b64_tr_b16 v[112:113], v65 offset:0x600
	ds_read_b64_tr_b16 v[114:115], v65 offset:0xe00
	v_mfma_f32_32x32x16_bf16 v[32:47], v[72:75], v[120:123], v[32:47]
	ds_read_b64_tr_b16 v[120:121], v65 offset:0x1600
	ds_read_b64_tr_b16 v[122:123], v65 offset:0x1e00
	v_mfma_f32_32x32x16_bf16 v[32:47], v[76:79], v[124:127], v[32:47]
	ds_read_b64_tr_b16 v[124:125], v65 offset:0x2600
	ds_read_b64_tr_b16 v[126:127], v65 offset:0x2e00
	ds_read_b64_tr_b16 v[132:133], v65 offset:0x3600
	ds_read_b64_tr_b16 v[134:135], v65 offset:0x3e00
	s_waitcnt lgkmcnt(0)
	v_mfma_f32_32x32x16_bf16 v[32:47], v[116:119], v[128:131], v[32:47]
	v_exp_f32_e32 v96, v96
	v_exp_f32_e32 v97, v97
	v_exp_f32_e32 v98, v98
	v_exp_f32_e32 v99, v99
	v_exp_f32_e32 v100, v100
	v_mfma_f32_32x32x16_bf16 v[48:63], v[68:71], v[112:115], v[48:63]
	v_add_f32_e32 v65, 0, v96
	v_exp_f32_e32 v101, v101
	v_add_f32_e32 v65, v97, v65
	v_exp_f32_e32 v71, v102
	v_add_f32_e32 v65, v98, v65
	v_exp_f32_e32 v102, v103
	v_add_f32_e32 v65, v99, v65
	v_exp_f32_e32 v103, v104
	v_add_f32_e32 v65, v100, v65
	v_exp_f32_e32 v104, v105
	v_add_f32_e32 v65, v101, v65
	v_exp_f32_e32 v105, v106
	v_add_f32_e32 v65, v71, v65
	v_exp_f32_e32 v106, v107
	v_add_f32_e32 v65, v102, v65
	v_exp_f32_e32 v107, v108
	v_mfma_f32_32x32x16_bf16 v[48:63], v[72:75], v[120:123], v[48:63]
	v_add_f32_e32 v65, v103, v65
	v_exp_f32_e32 v74, v109
	v_add_f32_e32 v65, v104, v65
	v_exp_f32_e32 v75, v110
	v_add_f32_e32 v65, v105, v65
	v_exp_f32_e32 v108, v111
	v_add_f32_e32 v65, v106, v65
	v_exp_f32_e32 v80, v80
	v_add_f32_e32 v65, v107, v65
	v_exp_f32_e32 v81, v81
	v_add_f32_e32 v65, v74, v65
	v_exp_f32_e32 v82, v82
	v_add_f32_e32 v65, v75, v65
	v_exp_f32_e32 v83, v83
	v_add_f32_e32 v65, v108, v65
	v_mfma_f32_32x32x16_bf16 v[48:63], v[76:79], v[124:127], v[48:63]
	v_exp_f32_e32 v78, v84
	v_add_f32_e32 v65, v80, v65
	v_exp_f32_e32 v79, v85
	v_add_f32_e32 v65, v81, v65
	v_exp_f32_e32 v84, v86
	v_add_f32_e32 v65, v82, v65
	v_exp_f32_e32 v85, v87
	v_add_f32_e32 v65, v83, v65
	v_exp_f32_e32 v86, v88
	v_add_f32_e32 v65, v78, v65
	v_exp_f32_e32 v87, v89
	v_add_f32_e32 v65, v79, v65
	v_exp_f32_e32 v88, v90
	v_add_f32_e32 v65, v84, v65
	v_exp_f32_e32 v89, v91
	v_add_f32_e32 v65, v85, v65
	v_exp_f32_e32 v90, v92
	v_add_f32_e32 v65, v86, v65
	v_exp_f32_e32 v91, v93
	v_add_f32_e32 v65, v87, v65
	v_mfma_f32_32x32x16_bf16 v[48:63], v[116:119], v[132:135], v[48:63]
	v_exp_f32_e32 v92, v94
	v_add_f32_e32 v65, v88, v65
	v_exp_f32_e32 v93, v95
	v_add_f32_e32 v65, v89, v65
	v_add_f32_e32 v65, v90, v65
	v_add_f32_e32 v65, v91, v65
	v_add_f32_e32 v65, v92, v65
	v_add_f32_e32 v65, v93, v65
	v_mov_b32_e32 v67, v65
	s_nop 1
	v_permlane32_swap_b32_e32 v65, v67
	v_cvt_pk_bf16_f32 v68, v96, v97
	v_cvt_pk_bf16_f32 v69, v98, v99
	v_cvt_pk_bf16_f32 v70, v100, v101
	v_cvt_pk_bf16_f32 v71, v71, v102
	v_cvt_pk_bf16_f32 v72, v103, v104
	v_cvt_pk_bf16_f32 v73, v105, v106
	v_cvt_pk_bf16_f32 v74, v107, v74
	v_cvt_pk_bf16_f32 v75, v75, v108
	v_cvt_pk_bf16_f32 v76, v80, v81
	v_cvt_pk_bf16_f32 v77, v82, v83
	v_cvt_pk_bf16_f32 v78, v78, v79
	v_cvt_pk_bf16_f32 v79, v84, v85
	v_cvt_pk_bf16_f32 v80, v86, v87
	v_cvt_pk_bf16_f32 v81, v88, v89
	v_cvt_pk_bf16_f32 v82, v90, v91
	v_cvt_pk_bf16_f32 v83, v92, v93
	s_nop 0
	ds_read_b64_tr_b16 v[84:85], v207 offset:0
	ds_read_b64_tr_b16 v[86:87], v207 offset:0x800
	ds_read_b64_tr_b16 v[88:89], v207 offset:0x1000
	ds_read_b64_tr_b16 v[90:91], v207 offset:0x1800
	ds_read_b64_tr_b16 v[92:93], v207 offset:0x2000
	ds_read_b64_tr_b16 v[94:95], v207 offset:0x2800
	ds_read_b64_tr_b16 v[96:97], v207 offset:0x3000
	ds_read_b64_tr_b16 v[98:99], v207 offset:0x3800
	s_waitcnt lgkmcnt(0)
	s_nop 0
	v_mfma_f32_32x32x16_bf16 v[0:15], v[68:71], v[84:87], v[0:15]
	ds_read_b64_tr_b16 v[84:85], v207 offset:0x200
	ds_read_b64_tr_b16 v[86:87], v207 offset:0xa00
	v_mfma_f32_32x32x16_bf16 v[0:15], v[72:75], v[88:91], v[0:15]
	ds_read_b64_tr_b16 v[88:89], v207 offset:0x1200
	ds_read_b64_tr_b16 v[90:91], v207 offset:0x1a00
	v_mfma_f32_32x32x16_bf16 v[0:15], v[76:79], v[92:95], v[0:15]
	ds_read_b64_tr_b16 v[92:93], v207 offset:0x2200
	ds_read_b64_tr_b16 v[94:95], v207 offset:0x2a00
	ds_read_b64_tr_b16 v[100:101], v207 offset:0x3200
	ds_read_b64_tr_b16 v[102:103], v207 offset:0x3a00
	s_waitcnt lgkmcnt(0)
	v_mfma_f32_32x32x16_bf16 v[0:15], v[80:83], v[96:99], v[0:15]
	v_mfma_f32_32x32x16_bf16 v[16:31], v[68:71], v[84:87], v[16:31]
	ds_read_b64_tr_b16 v[84:85], v207 offset:0x400
	ds_read_b64_tr_b16 v[86:87], v207 offset:0xc00
	v_mfma_f32_32x32x16_bf16 v[16:31], v[72:75], v[88:91], v[16:31]
	ds_read_b64_tr_b16 v[88:89], v207 offset:0x1400
	ds_read_b64_tr_b16 v[90:91], v207 offset:0x1c00
	v_mfma_f32_32x32x16_bf16 v[16:31], v[76:79], v[92:95], v[16:31]
	ds_read_b64_tr_b16 v[92:93], v207 offset:0x2400
	ds_read_b64_tr_b16 v[94:95], v207 offset:0x2c00
	ds_read_b64_tr_b16 v[96:97], v207 offset:0x3400
	ds_read_b64_tr_b16 v[98:99], v207 offset:0x3c00
	s_waitcnt lgkmcnt(0)
	v_mfma_f32_32x32x16_bf16 v[16:31], v[80:83], v[100:103], v[16:31]
	v_mfma_f32_32x32x16_bf16 v[32:47], v[68:71], v[84:87], v[32:47]
	ds_read_b64_tr_b16 v[84:85], v207 offset:0x600
	ds_read_b64_tr_b16 v[86:87], v207 offset:0xe00
	v_mfma_f32_32x32x16_bf16 v[32:47], v[72:75], v[88:91], v[32:47]
	ds_read_b64_tr_b16 v[88:89], v207 offset:0x1600
	ds_read_b64_tr_b16 v[90:91], v207 offset:0x1e00
	v_mfma_f32_32x32x16_bf16 v[32:47], v[76:79], v[92:95], v[32:47]
	ds_read_b64_tr_b16 v[92:93], v207 offset:0x2600
	ds_read_b64_tr_b16 v[94:95], v207 offset:0x2e00
	ds_read_b64_tr_b16 v[100:101], v207 offset:0x3600
	ds_read_b64_tr_b16 v[102:103], v207 offset:0x3e00
	s_waitcnt lgkmcnt(0)
	v_mfma_f32_32x32x16_bf16 v[32:47], v[80:83], v[96:99], v[32:47]
	v_mfma_f32_32x32x16_bf16 v[48:63], v[68:71], v[84:87], v[48:63]
	v_mfma_f32_32x32x16_bf16 v[48:63], v[72:75], v[88:91], v[48:63]
	v_mfma_f32_32x32x16_bf16 v[48:63], v[76:79], v[92:95], v[48:63]
	v_mfma_f32_32x32x16_bf16 v[48:63], v[80:83], v[100:103], v[48:63]
	s_and_saveexec_b64 s[14:15], s[4:5]
	s_cbranch_execz .LBB0_1084
	v_pk_add_f32 v[64:65], v[64:65], v[66:67]
	s_nop 0
	v_add_f32_e32 v64, v169, v64
	v_add_f32_e32 v64, v64, v65
	ds_write_b32 v191, v64
	s_branch .LBB0_1084
